# NSA_PACK compression GEMM loop: addresses before barrier, reads first, counted waits (same treatment as other GEMM loops)
# baseline (speedup 1.0000x reference)
.LBB0_596:
	s_mul_i32 s69, s13, 0x6000
	s_add_i32 s70, s69, 0xffffa000
	s_cmp_gt_i32 s13, 0
	s_cselect_b32 s74, s70, 0xc000
	s_lshr_b32 s75, s40, 1
	v_and_or_b32 v0, s43, 32, v143
	v_add_u32_e32 v149, s75, v144
	v_mad_i64_i32 v[194:195], s[70:71], v149, s16, v[130:131]
	v_lshlrev_b32_e32 v0, 1, v0
	v_lshl_add_u64 v[194:195], v[194:195], 0, v[0:1]
	v_lshl_add_u64 v[194:195], v[194:195], 0, s[66:67]
	v_add_u32_e32 v149, s75, v145
	v_mad_i64_i32 v[196:197], s[70:71], v149, s16, v[130:131]
	v_lshl_add_u64 v[196:197], v[196:197], 0, v[0:1]
	v_lshl_add_u64 v[196:197], v[196:197], 0, s[66:67]
	v_or_b32_e32 v0, s69, v147
	v_add_u32_e32 v0, v0, v146
	v_add3_u32 v212, s69, v148, v146
	s_waitcnt vmcnt(6)
	s_waitcnt lgkmcnt(0)
	s_barrier
	ds_read_b128 v[166:169], v212 offset:8192
	ds_read_b128 v[150:153], v0
	ds_read_b128 v[154:157], v0 offset:1024
	ds_read_b128 v[158:161], v0 offset:2048
	ds_read_b128 v[162:165], v0 offset:3072
	ds_read_b128 v[170:173], v212 offset:9216
	ds_read_b128 v[174:177], v212 offset:10240
	ds_read_b128 v[178:181], v212 offset:11264
	ds_read_b128 v[182:185], v212 offset:12288
	ds_read_b128 v[186:189], v212 offset:13312
	ds_read_b128 v[190:193], v212 offset:14336
	ds_read_b128 v[198:201], v212 offset:15360
	s_add_i32 s70, s74, s68
	s_mov_b32 m0, s70
	s_nop 0
	global_load_lds_dwordx4 v[194:195], off
	s_add_i32 s70, s74, s41
	s_mov_b32 m0, s70
	s_nop 0
	global_load_lds_dwordx4 v[196:197], off
	s_add_i32 s70, s42, s74
	s_mov_b32 m0, s70
	s_nop 0
	global_load_lds_dwordx4 v[138:139], off
	s_add_i32 s71, s70, 0x400
	s_mov_b32 m0, s71
	s_nop 0
	global_load_lds_dwordx4 v[136:137], off
	s_add_i32 s71, s70, 0x800
	s_mov_b32 m0, s71
	s_nop 0
	global_load_lds_dwordx4 v[134:135], off
	s_addk_i32 s70, 0xc00
	s_mov_b32 m0, s70
	s_nop 0
	global_load_lds_dwordx4 v[132:133], off
	s_waitcnt lgkmcnt(10)
	v_mfma_f32_16x16x32_bf16 v[126:129], v[166:169], v[150:153], v[126:129]
	s_waitcnt lgkmcnt(9)
	v_mfma_f32_16x16x32_bf16 v[122:125], v[166:169], v[154:157], v[122:125]
	s_waitcnt lgkmcnt(8)
	v_mfma_f32_16x16x32_bf16 v[118:121], v[166:169], v[158:161], v[118:121]
	s_waitcnt lgkmcnt(7)
	v_mfma_f32_16x16x32_bf16 v[114:117], v[166:169], v[162:165], v[114:117]
	s_waitcnt lgkmcnt(6)
	v_mfma_f32_16x16x32_bf16 v[110:113], v[170:173], v[150:153], v[110:113]
	v_mfma_f32_16x16x32_bf16 v[106:109], v[170:173], v[154:157], v[106:109]
	v_mfma_f32_16x16x32_bf16 v[102:105], v[170:173], v[158:161], v[102:105]
	v_mfma_f32_16x16x32_bf16 v[98:101], v[170:173], v[162:165], v[98:101]
	s_waitcnt lgkmcnt(5)
	v_mfma_f32_16x16x32_bf16 v[94:97], v[174:177], v[150:153], v[94:97]
	v_mfma_f32_16x16x32_bf16 v[90:93], v[174:177], v[154:157], v[90:93]
	v_mfma_f32_16x16x32_bf16 v[86:89], v[174:177], v[158:161], v[86:89]
	v_mfma_f32_16x16x32_bf16 v[82:85], v[174:177], v[162:165], v[82:85]
	s_waitcnt lgkmcnt(4)
	v_mfma_f32_16x16x32_bf16 v[78:81], v[178:181], v[150:153], v[78:81]
	v_mfma_f32_16x16x32_bf16 v[74:77], v[178:181], v[154:157], v[74:77]
	v_mfma_f32_16x16x32_bf16 v[70:73], v[178:181], v[158:161], v[70:73]
	v_mfma_f32_16x16x32_bf16 v[66:69], v[178:181], v[162:165], v[66:69]
	s_waitcnt lgkmcnt(3)
	v_mfma_f32_16x16x32_bf16 v[62:65], v[182:185], v[150:153], v[62:65]
	v_mfma_f32_16x16x32_bf16 v[58:61], v[182:185], v[154:157], v[58:61]
	v_mfma_f32_16x16x32_bf16 v[54:57], v[182:185], v[158:161], v[54:57]
	v_mfma_f32_16x16x32_bf16 v[50:53], v[182:185], v[162:165], v[50:53]
	s_waitcnt lgkmcnt(2)
	v_mfma_f32_16x16x32_bf16 v[46:49], v[186:189], v[150:153], v[46:49]
	v_mfma_f32_16x16x32_bf16 v[42:45], v[186:189], v[154:157], v[42:45]
	v_mfma_f32_16x16x32_bf16 v[38:41], v[186:189], v[158:161], v[38:41]
	v_mfma_f32_16x16x32_bf16 v[34:37], v[186:189], v[162:165], v[34:37]
	s_waitcnt lgkmcnt(1)
	v_mfma_f32_16x16x32_bf16 v[30:33], v[190:193], v[150:153], v[30:33]
	v_mfma_f32_16x16x32_bf16 v[26:29], v[190:193], v[154:157], v[26:29]
	v_mfma_f32_16x16x32_bf16 v[22:25], v[190:193], v[158:161], v[22:25]
	v_mfma_f32_16x16x32_bf16 v[18:21], v[190:193], v[162:165], v[18:21]
	s_waitcnt lgkmcnt(0)
	v_mfma_f32_16x16x32_bf16 v[14:17], v[198:201], v[150:153], v[14:17]
	v_mfma_f32_16x16x32_bf16 v[10:13], v[198:201], v[154:157], v[10:13]
	v_mfma_f32_16x16x32_bf16 v[6:9], v[198:201], v[158:161], v[6:9]
	v_mfma_f32_16x16x32_bf16 v[2:5], v[198:201], v[162:165], v[2:5]
	s_add_i32 s69, s13, 1
	s_cmp_lg_u32 s13, 2
	s_cselect_b32 s13, s69, 0
	s_add_i32 s40, s40, 1
	s_add_i32 s43, s43, 32
	v_lshl_add_u64 v[132:133], v[132:133], 0, 64
	v_lshl_add_u64 v[134:135], v[134:135], 0, 64
	v_lshl_add_u64 v[136:137], v[136:137], 0, 64
	s_cmp_eq_u32 s40, 64
	v_lshl_add_u64 v[138:139], v[138:139], 0, 64
	s_cbranch_scc0 .LBB0_596
	s_waitcnt vmcnt(6)
	v_add_u32_e32 v0, v148, v146
	s_waitcnt lgkmcnt(0)
	s_barrier
	ds_read_b128 v[130:133], v0 offset:64512
	ds_read_b128 v[134:137], v0 offset:63488
	ds_read_b128 v[148:151], v0 offset:62464
	ds_read_b128 v[152:155], v0 offset:61440
	ds_read_b128 v[156:159], v0 offset:60416
	ds_read_b128 v[160:163], v0 offset:59392
	ds_read_b128 v[164:167], v0 offset:58368
	ds_read_b128 v[168:171], v0 offset:57344
	v_add_u32_e32 v138, v147, v146
	ds_read_b128 v[144:147], v138 offset:52224
	ds_read_b128 v[172:175], v138 offset:51200
	ds_read_b128 v[176:179], v138 offset:50176
	ds_read_b128 v[180:183], v138 offset:49152
	s_lshl_b32 s40, s0, 8
	s_lshl_b64 s[0:1], s[0:1], 15
	s_ashr_i32 s41, s40, 31
	s_waitcnt lgkmcnt(0)
	v_mfma_f32_16x16x32_bf16 v[126:129], v[168:171], v[180:183], v[126:129]
	v_mfma_f32_16x16x32_bf16 v[46:49], v[148:151], v[180:183], v[46:49]
	v_mfma_f32_16x16x32_bf16 v[42:45], v[148:151], v[176:179], v[42:45]
	v_mfma_f32_16x16x32_bf16 v[38:41], v[148:151], v[172:175], v[38:41]
	v_mfma_f32_16x16x32_bf16 v[34:37], v[148:151], v[144:147], v[34:37]
	v_mfma_f32_16x16x32_bf16 v[30:33], v[134:137], v[180:183], v[30:33]
	v_mfma_f32_16x16x32_bf16 v[26:29], v[134:137], v[176:179], v[26:29]
	v_mfma_f32_16x16x32_bf16 v[22:25], v[134:137], v[172:175], v[22:25]
	v_mfma_f32_16x16x32_bf16 v[18:21], v[134:137], v[144:147], v[18:21]
	v_mfma_f32_16x16x32_bf16 v[14:17], v[130:133], v[180:183], v[14:17]
	v_mfma_f32_16x16x32_bf16 v[10:13], v[130:133], v[176:179], v[10:13]
	v_mfma_f32_16x16x32_bf16 v[6:9], v[130:133], v[172:175], v[6:9]
	v_mfma_f32_16x16x32_bf16 v[2:5], v[130:133], v[144:147], v[2:5]
	v_mfma_f32_16x16x32_bf16 v[122:125], v[168:171], v[176:179], v[122:125]
	v_mfma_f32_16x16x32_bf16 v[118:121], v[168:171], v[172:175], v[118:121]
	v_mfma_f32_16x16x32_bf16 v[114:117], v[168:171], v[144:147], v[114:117]
	v_mfma_f32_16x16x32_bf16 v[110:113], v[164:167], v[180:183], v[110:113]
	v_mfma_f32_16x16x32_bf16 v[106:109], v[164:167], v[176:179], v[106:109]
	v_mfma_f32_16x16x32_bf16 v[102:105], v[164:167], v[172:175], v[102:105]
	v_mfma_f32_16x16x32_bf16 v[98:101], v[164:167], v[144:147], v[98:101]
	v_mfma_f32_16x16x32_bf16 v[94:97], v[160:163], v[180:183], v[94:97]
	v_mfma_f32_16x16x32_bf16 v[90:93], v[160:163], v[176:179], v[90:93]
	v_mfma_f32_16x16x32_bf16 v[86:89], v[160:163], v[172:175], v[86:89]
	v_mfma_f32_16x16x32_bf16 v[82:85], v[160:163], v[144:147], v[82:85]
	v_mfma_f32_16x16x32_bf16 v[78:81], v[156:159], v[180:183], v[78:81]
	v_mfma_f32_16x16x32_bf16 v[74:77], v[156:159], v[176:179], v[74:77]
	v_mfma_f32_16x16x32_bf16 v[70:73], v[156:159], v[172:175], v[70:73]
	v_mfma_f32_16x16x32_bf16 v[66:69], v[156:159], v[144:147], v[66:69]
	v_mfma_f32_16x16x32_bf16 v[62:65], v[152:155], v[180:183], v[62:65]
	v_mfma_f32_16x16x32_bf16 v[58:61], v[152:155], v[176:179], v[58:61]
	v_mfma_f32_16x16x32_bf16 v[54:57], v[152:155], v[172:175], v[54:57]
	v_mfma_f32_16x16x32_bf16 v[50:53], v[152:155], v[144:147], v[50:53]
	s_waitcnt vmcnt(0)
	s_waitcnt lgkmcnt(0)
	s_barrier
	ds_read_b128 v[130:133], v138
	ds_read_b128 v[134:137], v138 offset:1024
	ds_read_b128 v[144:147], v138 offset:2048
	ds_read_b128 v[148:151], v138 offset:3072
	ds_read_b128 v[152:155], v0 offset:8192
	ds_read_b128 v[156:159], v0 offset:9216
	ds_read_b128 v[160:163], v0 offset:10240
	ds_read_b128 v[164:167], v0 offset:11264
	ds_read_b128 v[168:171], v0 offset:12288
	ds_read_b128 v[172:175], v0 offset:13312
	ds_read_b128 v[176:179], v0 offset:14336
	ds_read_b128 v[180:183], v0 offset:15360
	s_lshl_b64 s[40:41], s[40:41], 2
	s_add_u32 s42, s14, s40
	s_addc_u32 s43, s15, s41
	s_add_u32 s40, s53, s0
	s_addc_u32 s41, s54, s1
	s_waitcnt lgkmcnt(2)
	v_mfma_f32_16x16x32_bf16 v[46:49], v[172:175], v[130:133], v[46:49]
	v_mfma_f32_16x16x32_bf16 v[42:45], v[172:175], v[134:137], v[42:45]
	v_mfma_f32_16x16x32_bf16 v[38:41], v[172:175], v[144:147], v[38:41]
	v_mfma_f32_16x16x32_bf16 v[34:37], v[172:175], v[148:151], v[34:37]
	s_waitcnt lgkmcnt(1)
	v_mfma_f32_16x16x32_bf16 v[30:33], v[176:179], v[130:133], v[30:33]
	v_mfma_f32_16x16x32_bf16 v[26:29], v[176:179], v[134:137], v[26:29]
	v_mfma_f32_16x16x32_bf16 v[22:25], v[176:179], v[144:147], v[22:25]
	v_mfma_f32_16x16x32_bf16 v[18:21], v[176:179], v[148:151], v[18:21]
	s_waitcnt lgkmcnt(0)
	v_mfma_f32_16x16x32_bf16 v[14:17], v[180:183], v[130:133], v[14:17]
	v_mfma_f32_16x16x32_bf16 v[10:13], v[180:183], v[134:137], v[10:13]
	v_mfma_f32_16x16x32_bf16 v[6:9], v[180:183], v[144:147], v[6:9]
	v_mfma_f32_16x16x32_bf16 v[2:5], v[180:183], v[148:151], v[2:5]
	v_mfma_f32_16x16x32_bf16 v[184:187], v[152:155], v[130:133], v[126:129]
	v_mfma_f32_16x16x32_bf16 v[122:125], v[152:155], v[134:137], v[122:125]
	v_mfma_f32_16x16x32_bf16 v[188:191], v[152:155], v[144:147], v[118:121]
	v_mfma_f32_16x16x32_bf16 v[114:117], v[152:155], v[148:151], v[114:117]
	v_mfma_f32_16x16x32_bf16 v[110:113], v[156:159], v[130:133], v[110:113]
	v_mfma_f32_16x16x32_bf16 v[106:109], v[156:159], v[134:137], v[106:109]
	v_mfma_f32_16x16x32_bf16 v[102:105], v[156:159], v[144:147], v[102:105]
	v_mfma_f32_16x16x32_bf16 v[98:101], v[156:159], v[148:151], v[98:101]
	v_mfma_f32_16x16x32_bf16 v[94:97], v[160:163], v[130:133], v[94:97]
	v_mfma_f32_16x16x32_bf16 v[90:93], v[160:163], v[134:137], v[90:93]
	v_mfma_f32_16x16x32_bf16 v[86:89], v[160:163], v[144:147], v[86:89]
	v_mfma_f32_16x16x32_bf16 v[82:85], v[160:163], v[148:151], v[82:85]
	v_mfma_f32_16x16x32_bf16 v[78:81], v[164:167], v[130:133], v[78:81]
	v_mfma_f32_16x16x32_bf16 v[74:77], v[164:167], v[134:137], v[74:77]
	v_mfma_f32_16x16x32_bf16 v[70:73], v[164:167], v[144:147], v[70:73]
	v_mfma_f32_16x16x32_bf16 v[66:69], v[164:167], v[148:151], v[66:69]
	v_mfma_f32_16x16x32_bf16 v[62:65], v[168:171], v[130:133], v[62:65]
	v_mfma_f32_16x16x32_bf16 v[58:61], v[168:171], v[134:137], v[58:61]
	v_mfma_f32_16x16x32_bf16 v[54:57], v[168:171], v[144:147], v[54:57]
	v_mfma_f32_16x16x32_bf16 v[50:53], v[168:171], v[148:151], v[50:53]
	v_mov_b32_e32 v129, v224
	s_movk_i32 s0, 0xff80
	v_bfe_u32 v0, v129, 4, 2
	v_lshlrev_b32_e32 v128, 2, v0
	v_and_or_b32 v126, v129, s0, v128
	v_ashrrev_i32_e32 v127, 31, v126
	v_lshl_add_u64 v[118:119], v[126:127], 2, s[42:43]
	s_barrier
	global_load_dwordx4 v[132:135], v[118:119], off
	v_and_b32_e32 v138, 0x4f, v129
	v_lshlrev_b32_e32 v0, 4, v0
	s_movk_i32 s0, 0x210
	s_cmp_gt_u32 s57, 31
	s_waitcnt vmcnt(0)
	v_pk_add_f32 v[120:121], v[184:185], v[132:133]
	s_nop 0
	v_pk_mul_f32 v[130:131], v[120:121], v[120:121]
	v_pk_add_f32 v[122:123], v[122:123], v[132:133]
	v_fmamk_f32 v127, v130, 0xbdd2d3e2, v251
	v_mul_f32_e32 v127, v120, v127
	v_exp_f32_e32 v127, v127
	v_pk_add_f32 v[114:115], v[114:115], v[132:133]
	v_add_f32_e32 v127, 1.0, v127
	v_rcp_f32_e32 v130, v127
	v_fmamk_f32 v127, v131, 0xbdd2d3e2, v251
	v_mul_f32_e32 v127, v121, v127
	v_exp_f32_e32 v127, v127
	s_nop 0
	v_add_f32_e32 v127, 1.0, v127
	v_rcp_f32_e32 v131, v127
	v_mul_u32_u24_e32 v127, 0x210, v138
	v_pk_mul_f32 v[120:121], v[120:121], v[130:131]
	v_pk_add_f32 v[130:131], v[186:187], v[134:135]
	v_cvt_pk_bf16_f32 v120, v120, v121
	v_pk_mul_f32 v[136:137], v[130:131], v[130:131]
	s_nop 0
	v_fmamk_f32 v121, v136, 0xbdd2d3e2, v251
	v_mul_f32_e32 v121, v130, v121
	v_exp_f32_e32 v121, v121
	s_nop 0
	v_add_f32_e32 v121, 1.0, v121
	v_rcp_f32_e32 v136, v121
	v_fmamk_f32 v121, v137, 0xbdd2d3e2, v251
	v_mul_f32_e32 v121, v131, v121
	v_exp_f32_e32 v121, v121
	s_nop 0
	v_add_f32_e32 v121, 1.0, v121
	v_rcp_f32_e32 v137, v121
	s_nop 0
	v_pk_mul_f32 v[130:131], v[130:131], v[136:137]
	s_nop 0
	v_cvt_pk_bf16_f32 v121, v130, v131
	v_lshl_add_u32 v130, v126, 1, v127
	v_pk_mul_f32 v[126:127], v[122:123], v[122:123]
	s_nop 0
	v_fmamk_f32 v126, v126, 0xbdd2d3e2, v251
	v_fmamk_f32 v127, v127, 0xbdd2d3e2, v251
	v_mul_f32_e32 v126, v122, v126
	v_mul_f32_e32 v127, v123, v127
	v_exp_f32_e32 v126, v126
	v_exp_f32_e32 v127, v127
	v_add_f32_e32 v126, 1.0, v126
	v_add_f32_e32 v127, 1.0, v127
	v_rcp_f32_e32 v126, v126
	v_rcp_f32_e32 v127, v127
	s_nop 0
	v_pk_mul_f32 v[122:123], v[122:123], v[126:127]
	s_nop 0
	v_cvt_pk_bf16_f32 v126, v122, v123
	v_pk_add_f32 v[122:123], v[124:125], v[134:135]
	s_nop 0
	v_pk_mul_f32 v[124:125], v[122:123], v[122:123]
	s_nop 0
	v_fmamk_f32 v124, v124, 0xbdd2d3e2, v251
	v_fmamk_f32 v125, v125, 0xbdd2d3e2, v251
	v_mul_f32_e32 v124, v122, v124
	v_mul_f32_e32 v125, v123, v125
	v_exp_f32_e32 v124, v124
	v_exp_f32_e32 v125, v125
	v_add_f32_e32 v124, 1.0, v124
	v_add_f32_e32 v125, 1.0, v125
	v_rcp_f32_e32 v124, v124
	v_rcp_f32_e32 v125, v125
	s_nop 0
	v_pk_mul_f32 v[122:123], v[122:123], v[124:125]
	s_nop 0
	v_cvt_pk_bf16_f32 v127, v122, v123
	v_pk_add_f32 v[122:123], v[188:189], v[132:133]
	s_nop 0
	v_pk_mul_f32 v[124:125], v[122:123], v[122:123]
	s_nop 0
	v_fmamk_f32 v124, v124, 0xbdd2d3e2, v251
	v_fmamk_f32 v125, v125, 0xbdd2d3e2, v251
	v_mul_f32_e32 v124, v122, v124
	v_mul_f32_e32 v125, v123, v125
	v_exp_f32_e32 v124, v124
	v_exp_f32_e32 v125, v125
	v_add_f32_e32 v124, 1.0, v124
	v_add_f32_e32 v125, 1.0, v125
	v_rcp_f32_e32 v124, v124
	v_rcp_f32_e32 v125, v125
	s_nop 0
	v_pk_mul_f32 v[122:123], v[122:123], v[124:125]
	s_nop 0
	v_cvt_pk_bf16_f32 v124, v122, v123
	v_pk_add_f32 v[122:123], v[190:191], v[134:135]
	s_nop 0
	v_pk_mul_f32 v[136:137], v[122:123], v[122:123]
	s_nop 0
	v_fmamk_f32 v125, v136, 0xbdd2d3e2, v251
	v_mul_f32_e32 v125, v122, v125
	v_exp_f32_e32 v125, v125
	s_nop 0
	v_add_f32_e32 v125, 1.0, v125
	v_rcp_f32_e32 v136, v125
	v_fmamk_f32 v125, v137, 0xbdd2d3e2, v251
	v_mul_f32_e32 v125, v123, v125
	v_exp_f32_e32 v125, v125
	s_nop 0
	v_add_f32_e32 v125, 1.0, v125
	v_rcp_f32_e32 v137, v125
	s_nop 0
	v_pk_mul_f32 v[122:123], v[122:123], v[136:137]
	s_nop 0
	v_cvt_pk_bf16_f32 v125, v122, v123
	v_pk_mul_f32 v[122:123], v[114:115], v[114:115]
	s_nop 0
	v_fmamk_f32 v122, v122, 0xbdd2d3e2, v251
	v_fmamk_f32 v123, v123, 0xbdd2d3e2, v251
	v_mul_f32_e32 v122, v114, v122
	v_mul_f32_e32 v123, v115, v123
	v_exp_f32_e32 v122, v122
	v_exp_f32_e32 v123, v123
	v_add_f32_e32 v122, 1.0, v122
	v_add_f32_e32 v123, 1.0, v123
	v_rcp_f32_e32 v122, v122
	v_rcp_f32_e32 v123, v123
	s_nop 0
	v_pk_mul_f32 v[114:115], v[114:115], v[122:123]
	s_nop 0
	v_cvt_pk_bf16_f32 v122, v114, v115
	v_pk_add_f32 v[114:115], v[116:117], v[134:135]
	s_nop 0
	v_pk_mul_f32 v[116:117], v[114:115], v[114:115]
	s_nop 0
	v_fmamk_f32 v116, v116, 0xbdd2d3e2, v251
	v_fmamk_f32 v117, v117, 0xbdd2d3e2, v251
	v_mul_f32_e32 v116, v114, v116
	v_mul_f32_e32 v117, v115, v117
	v_exp_f32_e32 v116, v116
	v_exp_f32_e32 v117, v117
	v_add_f32_e32 v116, 1.0, v116
	v_add_f32_e32 v117, 1.0, v117
	v_rcp_f32_e32 v116, v116
	v_rcp_f32_e32 v117, v117
	s_nop 0
	v_pk_mul_f32 v[114:115], v[114:115], v[116:117]
	s_nop 0
	v_cvt_pk_bf16_f32 v123, v114, v115
	global_load_dwordx4 v[114:117], v[118:119], off offset:64
	s_waitcnt vmcnt(0)
	v_pk_add_f32 v[110:111], v[110:111], v[114:115]
	s_nop 0
	v_pk_mul_f32 v[132:133], v[110:111], v[110:111]
	v_pk_add_f32 v[112:113], v[112:113], v[116:117]
	v_fmamk_f32 v131, v132, 0xbdd2d3e2, v251
	v_mul_f32_e32 v131, v110, v131
	v_exp_f32_e32 v131, v131
	v_pk_add_f32 v[106:107], v[106:107], v[114:115]
	v_pk_add_f32 v[102:103], v[102:103], v[114:115]
	v_pk_add_f32 v[98:99], v[98:99], v[114:115]
	v_add_f32_e32 v131, 1.0, v131
	v_rcp_f32_e32 v132, v131
	v_fmamk_f32 v131, v133, 0xbdd2d3e2, v251
	v_mul_f32_e32 v131, v111, v131
	v_exp_f32_e32 v131, v131
	v_pk_add_f32 v[100:101], v[100:101], v[116:117]
	v_add_f32_e32 v131, 1.0, v131
	v_rcp_f32_e32 v133, v131
	s_nop 0
	v_pk_mul_f32 v[110:111], v[110:111], v[132:133]
	v_pk_mul_f32 v[132:133], v[112:113], v[112:113]
	v_cvt_pk_bf16_f32 v110, v110, v111
	v_fmamk_f32 v111, v132, 0xbdd2d3e2, v251
	v_mul_f32_e32 v111, v112, v111
	v_exp_f32_e32 v111, v111
	s_nop 0
	v_add_f32_e32 v111, 1.0, v111
	v_rcp_f32_e32 v132, v111
	v_fmamk_f32 v111, v133, 0xbdd2d3e2, v251
	v_mul_f32_e32 v111, v113, v111
	v_exp_f32_e32 v111, v111
	s_nop 0
	v_add_f32_e32 v111, 1.0, v111
	v_rcp_f32_e32 v133, v111
	s_nop 0
	v_pk_mul_f32 v[112:113], v[112:113], v[132:133]
	s_nop 0
	v_cvt_pk_bf16_f32 v111, v112, v113
	ds_write2_b64 v130, v[120:121], v[110:111] offset1:4
	v_pk_mul_f32 v[110:111], v[106:107], v[106:107]
	s_nop 0
	v_fmamk_f32 v110, v110, 0xbdd2d3e2, v251
	v_fmamk_f32 v111, v111, 0xbdd2d3e2, v251
	v_mul_f32_e32 v110, v106, v110
	v_mul_f32_e32 v111, v107, v111
	v_exp_f32_e32 v110, v110
	v_exp_f32_e32 v111, v111
	v_add_f32_e32 v110, 1.0, v110
	v_add_f32_e32 v111, 1.0, v111
	v_rcp_f32_e32 v110, v110
	v_rcp_f32_e32 v111, v111
	s_nop 0
	v_pk_mul_f32 v[106:107], v[106:107], v[110:111]
	s_nop 0
	v_cvt_pk_bf16_f32 v110, v106, v107
	v_pk_add_f32 v[106:107], v[108:109], v[116:117]
	s_nop 0
	v_pk_mul_f32 v[108:109], v[106:107], v[106:107]
	s_nop 0
	v_fmamk_f32 v108, v108, 0xbdd2d3e2, v251
	v_fmamk_f32 v109, v109, 0xbdd2d3e2, v251
	v_mul_f32_e32 v108, v106, v108
	v_mul_f32_e32 v109, v107, v109
	v_exp_f32_e32 v108, v108
	v_exp_f32_e32 v109, v109
	v_add_f32_e32 v108, 1.0, v108
	v_add_f32_e32 v109, 1.0, v109
	v_rcp_f32_e32 v108, v108
	v_rcp_f32_e32 v109, v109
	s_nop 0
	v_pk_mul_f32 v[106:107], v[106:107], v[108:109]
	v_pk_mul_f32 v[108:109], v[102:103], v[102:103]
	v_cvt_pk_bf16_f32 v111, v106, v107
	v_fmamk_f32 v107, v108, 0xbdd2d3e2, v251
	v_mul_f32_e32 v107, v102, v107
	v_exp_f32_e32 v107, v107
	v_add_u32_e32 v106, 0x2000, v130
	ds_write2_b64 v106, v[126:127], v[110:111] offset0:32 offset1:36
	v_add_f32_e32 v107, 1.0, v107
	v_rcp_f32_e32 v108, v107
	v_fmamk_f32 v107, v109, 0xbdd2d3e2, v251
	v_mul_f32_e32 v107, v103, v107
	v_exp_f32_e32 v107, v107
	s_nop 0
	v_add_f32_e32 v107, 1.0, v107
	v_rcp_f32_e32 v109, v107
	s_nop 0
	v_pk_mul_f32 v[102:103], v[102:103], v[108:109]
	s_nop 0
	v_cvt_pk_bf16_f32 v108, v102, v103
	v_pk_add_f32 v[102:103], v[104:105], v[116:117]
	s_nop 0
	v_pk_mul_f32 v[104:105], v[102:103], v[102:103]
	s_nop 0
	v_fmamk_f32 v104, v104, 0xbdd2d3e2, v251
	v_fmamk_f32 v105, v105, 0xbdd2d3e2, v251
	v_mul_f32_e32 v104, v102, v104
	v_mul_f32_e32 v105, v103, v105
	v_exp_f32_e32 v104, v104
	v_exp_f32_e32 v105, v105
	v_add_f32_e32 v104, 1.0, v104
	v_add_f32_e32 v105, 1.0, v105
	v_rcp_f32_e32 v104, v104
	v_rcp_f32_e32 v105, v105
	s_nop 0
	v_pk_mul_f32 v[102:103], v[102:103], v[104:105]
	s_nop 0
	v_cvt_pk_bf16_f32 v109, v102, v103
	v_add_u32_e32 v102, 0x4000, v130
	ds_write2_b64 v102, v[124:125], v[108:109] offset0:64 offset1:68
	global_load_dwordx4 v[108:111], v[118:119], off offset:128
	v_pk_mul_f32 v[104:105], v[98:99], v[98:99]
	s_waitcnt vmcnt(0)
	v_pk_add_f32 v[94:95], v[94:95], v[108:109]
	v_fmamk_f32 v103, v104, 0xbdd2d3e2, v251
	v_mul_f32_e32 v103, v98, v103
	v_exp_f32_e32 v103, v103
	v_pk_add_f32 v[90:91], v[90:91], v[108:109]
	v_pk_add_f32 v[86:87], v[86:87], v[108:109]
	v_pk_add_f32 v[82:83], v[82:83], v[108:109]
	v_add_f32_e32 v103, 1.0, v103
	v_rcp_f32_e32 v104, v103
	v_fmamk_f32 v103, v105, 0xbdd2d3e2, v251
	v_mul_f32_e32 v103, v99, v103
	v_exp_f32_e32 v103, v103
	s_nop 0
	v_add_f32_e32 v103, 1.0, v103
	v_rcp_f32_e32 v105, v103
	s_nop 0
	v_pk_mul_f32 v[98:99], v[98:99], v[104:105]
	v_pk_mul_f32 v[104:105], v[100:101], v[100:101]
	v_cvt_pk_bf16_f32 v98, v98, v99
	v_fmamk_f32 v99, v104, 0xbdd2d3e2, v251
	v_mul_f32_e32 v99, v100, v99
	v_exp_f32_e32 v99, v99
	s_nop 0
	v_add_f32_e32 v99, 1.0, v99
	v_rcp_f32_e32 v104, v99
	v_fmamk_f32 v99, v105, 0xbdd2d3e2, v251
	v_mul_f32_e32 v99, v101, v99
	v_exp_f32_e32 v99, v99
	s_nop 0
	v_add_f32_e32 v99, 1.0, v99
	v_rcp_f32_e32 v105, v99
	s_nop 0
	v_pk_mul_f32 v[100:101], v[100:101], v[104:105]
	s_nop 0
	v_cvt_pk_bf16_f32 v99, v100, v101
	v_add_u32_e32 v100, 0x6000, v130
	ds_write2_b64 v100, v[122:123], v[98:99] offset0:96 offset1:100
	v_pk_mul_f32 v[98:99], v[94:95], v[94:95]
	s_nop 0
	v_fmamk_f32 v98, v98, 0xbdd2d3e2, v251
	v_fmamk_f32 v99, v99, 0xbdd2d3e2, v251
	v_mul_f32_e32 v98, v94, v98
	v_mul_f32_e32 v99, v95, v99
	v_exp_f32_e32 v98, v98
	v_exp_f32_e32 v99, v99
	v_add_f32_e32 v98, 1.0, v98
	v_add_f32_e32 v99, 1.0, v99
	v_rcp_f32_e32 v98, v98
	v_rcp_f32_e32 v99, v99
	s_nop 0
	v_pk_mul_f32 v[94:95], v[94:95], v[98:99]
	s_nop 0
	v_cvt_pk_bf16_f32 v98, v94, v95
	v_pk_add_f32 v[94:95], v[96:97], v[110:111]
	s_nop 0
	v_pk_mul_f32 v[96:97], v[94:95], v[94:95]
	s_nop 0
	v_fmamk_f32 v96, v96, 0xbdd2d3e2, v251
	v_fmamk_f32 v97, v97, 0xbdd2d3e2, v251
	v_mul_f32_e32 v96, v94, v96
	v_mul_f32_e32 v97, v95, v97
	v_exp_f32_e32 v96, v96
	v_exp_f32_e32 v97, v97
	v_add_f32_e32 v96, 1.0, v96
	v_add_f32_e32 v97, 1.0, v97
	v_rcp_f32_e32 v96, v96
	v_rcp_f32_e32 v97, v97
	s_nop 0
	v_pk_mul_f32 v[94:95], v[94:95], v[96:97]
	s_nop 0
	v_cvt_pk_bf16_f32 v99, v94, v95
	v_pk_mul_f32 v[94:95], v[90:91], v[90:91]
	s_nop 0
	v_fmamk_f32 v94, v94, 0xbdd2d3e2, v251
	v_fmamk_f32 v95, v95, 0xbdd2d3e2, v251
	v_mul_f32_e32 v94, v90, v94
	v_mul_f32_e32 v95, v91, v95
	v_exp_f32_e32 v94, v94
	v_exp_f32_e32 v95, v95
	v_add_f32_e32 v94, 1.0, v94
	v_add_f32_e32 v95, 1.0, v95
	v_rcp_f32_e32 v94, v94
	v_rcp_f32_e32 v95, v95
	s_nop 0
	v_pk_mul_f32 v[90:91], v[90:91], v[94:95]
	s_nop 0
	v_cvt_pk_bf16_f32 v94, v90, v91
	v_pk_add_f32 v[90:91], v[92:93], v[110:111]
	s_nop 0
	v_pk_mul_f32 v[92:93], v[90:91], v[90:91]
	s_nop 0
	v_fmamk_f32 v92, v92, 0xbdd2d3e2, v251
	v_fmamk_f32 v93, v93, 0xbdd2d3e2, v251
	v_mul_f32_e32 v92, v90, v92
	v_mul_f32_e32 v93, v91, v93
	v_exp_f32_e32 v92, v92
	v_exp_f32_e32 v93, v93
	v_add_f32_e32 v92, 1.0, v92
	v_add_f32_e32 v93, 1.0, v93
	v_rcp_f32_e32 v92, v92
	v_rcp_f32_e32 v93, v93
	s_nop 0
	v_pk_mul_f32 v[90:91], v[90:91], v[92:93]
	s_nop 0
	v_cvt_pk_bf16_f32 v95, v90, v91
	v_pk_mul_f32 v[90:91], v[86:87], v[86:87]
	s_nop 0
	v_fmamk_f32 v90, v90, 0xbdd2d3e2, v251
	v_fmamk_f32 v91, v91, 0xbdd2d3e2, v251
	v_mul_f32_e32 v90, v86, v90
	v_mul_f32_e32 v91, v87, v91
	v_exp_f32_e32 v90, v90
	v_exp_f32_e32 v91, v91
	v_add_f32_e32 v90, 1.0, v90
	v_add_f32_e32 v91, 1.0, v91
	v_rcp_f32_e32 v90, v90
	v_rcp_f32_e32 v91, v91
	s_nop 0
	v_pk_mul_f32 v[86:87], v[86:87], v[90:91]
	s_nop 0
	v_cvt_pk_bf16_f32 v90, v86, v87
	v_pk_add_f32 v[86:87], v[88:89], v[110:111]
	s_nop 0
	v_pk_mul_f32 v[88:89], v[86:87], v[86:87]
	s_nop 0
	v_fmamk_f32 v88, v88, 0xbdd2d3e2, v251
	v_fmamk_f32 v89, v89, 0xbdd2d3e2, v251
	v_mul_f32_e32 v88, v86, v88
	v_mul_f32_e32 v89, v87, v89
	v_exp_f32_e32 v88, v88
	v_exp_f32_e32 v89, v89
	v_add_f32_e32 v88, 1.0, v88
	v_add_f32_e32 v89, 1.0, v89
	v_rcp_f32_e32 v88, v88
	v_rcp_f32_e32 v89, v89
	s_nop 0
	v_pk_mul_f32 v[86:87], v[86:87], v[88:89]
	s_nop 0
	v_cvt_pk_bf16_f32 v91, v86, v87
	v_pk_mul_f32 v[86:87], v[82:83], v[82:83]
	s_nop 0
	v_fmamk_f32 v86, v86, 0xbdd2d3e2, v251
	v_fmamk_f32 v87, v87, 0xbdd2d3e2, v251
	v_mul_f32_e32 v86, v82, v86
	v_mul_f32_e32 v87, v83, v87
	v_exp_f32_e32 v86, v86
	v_exp_f32_e32 v87, v87
	v_add_f32_e32 v86, 1.0, v86
	v_add_f32_e32 v87, 1.0, v87
	v_rcp_f32_e32 v86, v86
	v_rcp_f32_e32 v87, v87
	s_nop 0
	v_pk_mul_f32 v[82:83], v[82:83], v[86:87]
	s_nop 0
	v_cvt_pk_bf16_f32 v86, v82, v83
	v_pk_add_f32 v[82:83], v[84:85], v[110:111]
	s_nop 0
	v_pk_mul_f32 v[84:85], v[82:83], v[82:83]
	s_nop 0
	v_fmamk_f32 v84, v84, 0xbdd2d3e2, v251
	v_fmamk_f32 v85, v85, 0xbdd2d3e2, v251
	v_mul_f32_e32 v84, v82, v84
	v_mul_f32_e32 v85, v83, v85
	v_exp_f32_e32 v84, v84
	v_exp_f32_e32 v85, v85
	v_add_f32_e32 v84, 1.0, v84
	v_add_f32_e32 v85, 1.0, v85
	v_rcp_f32_e32 v84, v84
	v_rcp_f32_e32 v85, v85
	s_nop 0
	v_pk_mul_f32 v[82:83], v[82:83], v[84:85]
	s_nop 0
	v_cvt_pk_bf16_f32 v87, v82, v83
	global_load_dwordx4 v[82:85], v[118:119], off offset:192
	s_waitcnt vmcnt(0)
	v_pk_add_f32 v[78:79], v[78:79], v[82:83]
	s_nop 0
	v_pk_mul_f32 v[88:89], v[78:79], v[78:79]
	v_pk_add_f32 v[80:81], v[80:81], v[84:85]
	v_fmamk_f32 v88, v88, 0xbdd2d3e2, v251
	v_fmamk_f32 v89, v89, 0xbdd2d3e2, v251
	v_mul_f32_e32 v88, v78, v88
	v_mul_f32_e32 v89, v79, v89
	v_exp_f32_e32 v88, v88
	v_exp_f32_e32 v89, v89
	v_pk_add_f32 v[74:75], v[74:75], v[82:83]
	v_pk_add_f32 v[76:77], v[76:77], v[84:85]
	v_add_f32_e32 v88, 1.0, v88
	v_add_f32_e32 v89, 1.0, v89
	v_rcp_f32_e32 v88, v88
	v_rcp_f32_e32 v89, v89
	v_pk_add_f32 v[70:71], v[70:71], v[82:83]
	v_pk_add_f32 v[72:73], v[72:73], v[84:85]
	v_pk_add_f32 v[66:67], v[66:67], v[82:83]
	v_pk_mul_f32 v[78:79], v[78:79], v[88:89]
	v_pk_mul_f32 v[88:89], v[80:81], v[80:81]
	v_cvt_pk_bf16_f32 v78, v78, v79
	v_fmamk_f32 v79, v88, 0xbdd2d3e2, v251
	v_mul_f32_e32 v79, v80, v79
	v_exp_f32_e32 v79, v79
	v_pk_add_f32 v[68:69], v[68:69], v[84:85]
	v_add_f32_e32 v79, 1.0, v79
	v_rcp_f32_e32 v88, v79
	v_fmamk_f32 v79, v89, 0xbdd2d3e2, v251
	v_mul_f32_e32 v79, v81, v79
	v_exp_f32_e32 v79, v79
	s_nop 0
	v_add_f32_e32 v79, 1.0, v79
	v_rcp_f32_e32 v89, v79
	s_nop 0
	v_pk_mul_f32 v[80:81], v[80:81], v[88:89]
	s_nop 0
	v_cvt_pk_bf16_f32 v79, v80, v81
	ds_write2_b64 v130, v[98:99], v[78:79] offset0:8 offset1:12
	v_pk_mul_f32 v[78:79], v[74:75], v[74:75]
	s_nop 0
	v_fmamk_f32 v78, v78, 0xbdd2d3e2, v251
	v_fmamk_f32 v79, v79, 0xbdd2d3e2, v251
	v_mul_f32_e32 v78, v74, v78
	v_mul_f32_e32 v79, v75, v79
	v_exp_f32_e32 v78, v78
	v_exp_f32_e32 v79, v79
	v_add_f32_e32 v78, 1.0, v78
	v_add_f32_e32 v79, 1.0, v79
	v_rcp_f32_e32 v78, v78
	v_rcp_f32_e32 v79, v79
	s_nop 0
	v_pk_mul_f32 v[74:75], v[74:75], v[78:79]
	v_pk_mul_f32 v[78:79], v[76:77], v[76:77]
	v_cvt_pk_bf16_f32 v74, v74, v75
	v_fmamk_f32 v75, v78, 0xbdd2d3e2, v251
	v_mul_f32_e32 v75, v76, v75
	v_exp_f32_e32 v75, v75
	s_nop 0
	v_add_f32_e32 v75, 1.0, v75
	v_rcp_f32_e32 v78, v75
	v_fmamk_f32 v75, v79, 0xbdd2d3e2, v251
	v_mul_f32_e32 v75, v77, v75
	v_exp_f32_e32 v75, v75
	s_nop 0
	v_add_f32_e32 v75, 1.0, v75
	v_rcp_f32_e32 v79, v75
	s_nop 0
	v_pk_mul_f32 v[76:77], v[76:77], v[78:79]
	s_nop 0
	v_cvt_pk_bf16_f32 v75, v76, v77
	ds_write2_b64 v106, v[94:95], v[74:75] offset0:40 offset1:44
	v_pk_mul_f32 v[74:75], v[70:71], v[70:71]
	s_nop 0
	v_fmamk_f32 v74, v74, 0xbdd2d3e2, v251
	v_fmamk_f32 v75, v75, 0xbdd2d3e2, v251
	v_mul_f32_e32 v74, v70, v74
	v_mul_f32_e32 v75, v71, v75
	v_exp_f32_e32 v74, v74
	v_exp_f32_e32 v75, v75
	v_add_f32_e32 v74, 1.0, v74
	v_add_f32_e32 v75, 1.0, v75
	v_rcp_f32_e32 v74, v74
	v_rcp_f32_e32 v75, v75
	s_nop 0
	v_pk_mul_f32 v[70:71], v[70:71], v[74:75]
	v_pk_mul_f32 v[74:75], v[72:73], v[72:73]
	v_cvt_pk_bf16_f32 v70, v70, v71
	v_fmamk_f32 v71, v74, 0xbdd2d3e2, v251
	v_mul_f32_e32 v71, v72, v71
	v_exp_f32_e32 v71, v71
	s_nop 0
	v_add_f32_e32 v71, 1.0, v71
	v_rcp_f32_e32 v74, v71
	v_fmamk_f32 v71, v75, 0xbdd2d3e2, v251
	v_mul_f32_e32 v71, v73, v71
	v_exp_f32_e32 v71, v71
	s_nop 0
	v_add_f32_e32 v71, 1.0, v71
	v_rcp_f32_e32 v75, v71
	s_nop 0
	v_pk_mul_f32 v[72:73], v[72:73], v[74:75]
	s_nop 0
	v_cvt_pk_bf16_f32 v71, v72, v73
	ds_write2_b64 v102, v[90:91], v[70:71] offset0:72 offset1:76
	v_pk_mul_f32 v[70:71], v[66:67], v[66:67]
	s_nop 0
	v_fmamk_f32 v70, v70, 0xbdd2d3e2, v251
	v_fmamk_f32 v71, v71, 0xbdd2d3e2, v251
	v_mul_f32_e32 v70, v66, v70
	v_mul_f32_e32 v71, v67, v71
	v_exp_f32_e32 v70, v70
	v_exp_f32_e32 v71, v71
	v_add_f32_e32 v70, 1.0, v70
	v_add_f32_e32 v71, 1.0, v71
	v_rcp_f32_e32 v70, v70
	v_rcp_f32_e32 v71, v71
	s_nop 0
	v_pk_mul_f32 v[66:67], v[66:67], v[70:71]
	v_pk_mul_f32 v[70:71], v[68:69], v[68:69]
	v_cvt_pk_bf16_f32 v66, v66, v67
	v_fmamk_f32 v67, v70, 0xbdd2d3e2, v251
	v_mul_f32_e32 v67, v68, v67
	v_exp_f32_e32 v67, v67
	s_nop 0
	v_add_f32_e32 v67, 1.0, v67
	v_rcp_f32_e32 v70, v67
	v_fmamk_f32 v67, v71, 0xbdd2d3e2, v251
	v_mul_f32_e32 v67, v69, v67
	v_exp_f32_e32 v67, v67
	s_nop 0
	v_add_f32_e32 v67, 1.0, v67
	v_rcp_f32_e32 v71, v67
	s_nop 0
	v_pk_mul_f32 v[68:69], v[68:69], v[70:71]
	s_nop 0
	v_cvt_pk_bf16_f32 v67, v68, v69
	global_load_dwordx4 v[68:71], v[118:119], off offset:256
	ds_write2_b64 v100, v[86:87], v[66:67] offset0:104 offset1:108
	s_waitcnt vmcnt(0)
	v_pk_add_f32 v[62:63], v[62:63], v[68:69]
	s_nop 0
	v_pk_mul_f32 v[66:67], v[62:63], v[62:63]
	v_pk_add_f32 v[58:59], v[58:59], v[68:69]
	v_fmamk_f32 v66, v66, 0xbdd2d3e2, v251
	v_fmamk_f32 v67, v67, 0xbdd2d3e2, v251
	v_mul_f32_e32 v66, v62, v66
	v_mul_f32_e32 v67, v63, v67
	v_exp_f32_e32 v66, v66
	v_exp_f32_e32 v67, v67
	v_pk_add_f32 v[54:55], v[54:55], v[68:69]
	v_pk_add_f32 v[50:51], v[50:51], v[68:69]
	v_add_f32_e32 v66, 1.0, v66
	v_add_f32_e32 v67, 1.0, v67
	v_rcp_f32_e32 v66, v66
	v_rcp_f32_e32 v67, v67
	s_nop 0
	v_pk_mul_f32 v[62:63], v[62:63], v[66:67]
	s_nop 0
	v_cvt_pk_bf16_f32 v66, v62, v63
	v_pk_add_f32 v[62:63], v[64:65], v[70:71]
	s_nop 0
	v_pk_mul_f32 v[64:65], v[62:63], v[62:63]
	s_nop 0
	v_fmamk_f32 v64, v64, 0xbdd2d3e2, v251
	v_fmamk_f32 v65, v65, 0xbdd2d3e2, v251
	v_mul_f32_e32 v64, v62, v64
	v_mul_f32_e32 v65, v63, v65
	v_exp_f32_e32 v64, v64
	v_exp_f32_e32 v65, v65
	v_add_f32_e32 v64, 1.0, v64
	v_add_f32_e32 v65, 1.0, v65
	v_rcp_f32_e32 v64, v64
	v_rcp_f32_e32 v65, v65
	s_nop 0
	v_pk_mul_f32 v[62:63], v[62:63], v[64:65]
	s_nop 0
	v_cvt_pk_bf16_f32 v67, v62, v63
	v_pk_mul_f32 v[62:63], v[58:59], v[58:59]
	s_nop 0
	v_fmamk_f32 v62, v62, 0xbdd2d3e2, v251
	v_fmamk_f32 v63, v63, 0xbdd2d3e2, v251
	v_mul_f32_e32 v62, v58, v62
	v_mul_f32_e32 v63, v59, v63
	v_exp_f32_e32 v62, v62
	v_exp_f32_e32 v63, v63
	v_add_f32_e32 v62, 1.0, v62
	v_add_f32_e32 v63, 1.0, v63
	v_rcp_f32_e32 v62, v62
	v_rcp_f32_e32 v63, v63
	s_nop 0
	v_pk_mul_f32 v[58:59], v[58:59], v[62:63]
	s_nop 0
	v_cvt_pk_bf16_f32 v62, v58, v59
	v_pk_add_f32 v[58:59], v[60:61], v[70:71]
	s_nop 0
	v_pk_mul_f32 v[60:61], v[58:59], v[58:59]
	s_nop 0
	v_fmamk_f32 v60, v60, 0xbdd2d3e2, v251
	v_fmamk_f32 v61, v61, 0xbdd2d3e2, v251
	v_mul_f32_e32 v60, v58, v60
	v_mul_f32_e32 v61, v59, v61
	v_exp_f32_e32 v60, v60
	v_exp_f32_e32 v61, v61
	v_add_f32_e32 v60, 1.0, v60
	v_add_f32_e32 v61, 1.0, v61
	v_rcp_f32_e32 v60, v60
	v_rcp_f32_e32 v61, v61
	s_nop 0
	v_pk_mul_f32 v[58:59], v[58:59], v[60:61]
	s_nop 0
	v_cvt_pk_bf16_f32 v63, v58, v59
	v_pk_mul_f32 v[58:59], v[54:55], v[54:55]
	s_nop 0
	v_fmamk_f32 v58, v58, 0xbdd2d3e2, v251
	v_fmamk_f32 v59, v59, 0xbdd2d3e2, v251
	v_mul_f32_e32 v58, v54, v58
	v_mul_f32_e32 v59, v55, v59
	v_exp_f32_e32 v58, v58
	v_exp_f32_e32 v59, v59
	v_add_f32_e32 v58, 1.0, v58
	v_add_f32_e32 v59, 1.0, v59
	v_rcp_f32_e32 v58, v58
	v_rcp_f32_e32 v59, v59
	s_nop 0
	v_pk_mul_f32 v[54:55], v[54:55], v[58:59]
	s_nop 0
	v_cvt_pk_bf16_f32 v58, v54, v55
	v_pk_add_f32 v[54:55], v[56:57], v[70:71]
	s_nop 0
	v_pk_mul_f32 v[56:57], v[54:55], v[54:55]
	s_nop 0
	v_fmamk_f32 v56, v56, 0xbdd2d3e2, v251
	v_fmamk_f32 v57, v57, 0xbdd2d3e2, v251
	v_mul_f32_e32 v56, v54, v56
	v_mul_f32_e32 v57, v55, v57
	v_exp_f32_e32 v56, v56
	v_exp_f32_e32 v57, v57
	v_add_f32_e32 v56, 1.0, v56
	v_add_f32_e32 v57, 1.0, v57
	v_rcp_f32_e32 v56, v56
	v_rcp_f32_e32 v57, v57
	s_nop 0
	v_pk_mul_f32 v[54:55], v[54:55], v[56:57]
	s_nop 0
	v_cvt_pk_bf16_f32 v59, v54, v55
	v_pk_mul_f32 v[54:55], v[50:51], v[50:51]
	s_nop 0
	v_fmamk_f32 v54, v54, 0xbdd2d3e2, v251
	v_fmamk_f32 v55, v55, 0xbdd2d3e2, v251
	v_mul_f32_e32 v54, v50, v54
	v_mul_f32_e32 v55, v51, v55
	v_exp_f32_e32 v54, v54
	v_exp_f32_e32 v55, v55
	v_add_f32_e32 v54, 1.0, v54
	v_add_f32_e32 v55, 1.0, v55
	v_rcp_f32_e32 v54, v54
	v_rcp_f32_e32 v55, v55
	s_nop 0
	v_pk_mul_f32 v[50:51], v[50:51], v[54:55]
	s_nop 0
	v_cvt_pk_bf16_f32 v54, v50, v51
	v_pk_add_f32 v[50:51], v[52:53], v[70:71]
	s_nop 0
	v_pk_mul_f32 v[52:53], v[50:51], v[50:51]
	s_nop 0
	v_fmamk_f32 v52, v52, 0xbdd2d3e2, v251
	v_fmamk_f32 v53, v53, 0xbdd2d3e2, v251
	v_mul_f32_e32 v52, v50, v52
	v_mul_f32_e32 v53, v51, v53
	v_exp_f32_e32 v52, v52
	v_exp_f32_e32 v53, v53
	v_add_f32_e32 v52, 1.0, v52
	v_add_f32_e32 v53, 1.0, v53
	v_rcp_f32_e32 v52, v52
	v_rcp_f32_e32 v53, v53
	s_nop 0
	v_pk_mul_f32 v[50:51], v[50:51], v[52:53]
	s_nop 0
	v_cvt_pk_bf16_f32 v55, v50, v51
	global_load_dwordx4 v[50:53], v[118:119], off offset:320
	s_waitcnt vmcnt(0)
	v_pk_add_f32 v[46:47], v[46:47], v[50:51]
	s_nop 0
	v_pk_mul_f32 v[56:57], v[46:47], v[46:47]
	v_pk_add_f32 v[48:49], v[48:49], v[52:53]
	v_fmamk_f32 v56, v56, 0xbdd2d3e2, v251
	v_fmamk_f32 v57, v57, 0xbdd2d3e2, v251
	v_mul_f32_e32 v56, v46, v56
	v_mul_f32_e32 v57, v47, v57
	v_exp_f32_e32 v56, v56
	v_exp_f32_e32 v57, v57
	v_pk_add_f32 v[42:43], v[42:43], v[50:51]
	v_pk_add_f32 v[44:45], v[44:45], v[52:53]
	v_add_f32_e32 v56, 1.0, v56
	v_add_f32_e32 v57, 1.0, v57
	v_rcp_f32_e32 v56, v56
	v_rcp_f32_e32 v57, v57
	v_pk_add_f32 v[38:39], v[38:39], v[50:51]
	v_pk_add_f32 v[40:41], v[40:41], v[52:53]
	v_pk_add_f32 v[34:35], v[34:35], v[50:51]
	v_pk_mul_f32 v[46:47], v[46:47], v[56:57]
	v_pk_mul_f32 v[56:57], v[48:49], v[48:49]
	v_cvt_pk_bf16_f32 v46, v46, v47
	v_fmamk_f32 v47, v56, 0xbdd2d3e2, v251
	v_mul_f32_e32 v47, v48, v47
	v_exp_f32_e32 v47, v47
	v_pk_add_f32 v[36:37], v[36:37], v[52:53]
	v_add_f32_e32 v47, 1.0, v47
	v_rcp_f32_e32 v56, v47
	v_fmamk_f32 v47, v57, 0xbdd2d3e2, v251
	v_mul_f32_e32 v47, v49, v47
	v_exp_f32_e32 v47, v47
	s_nop 0
	v_add_f32_e32 v47, 1.0, v47
	v_rcp_f32_e32 v57, v47
	s_nop 0
	v_pk_mul_f32 v[48:49], v[48:49], v[56:57]
	s_nop 0
	v_cvt_pk_bf16_f32 v47, v48, v49
	ds_write2_b64 v130, v[66:67], v[46:47] offset0:16 offset1:20
	v_pk_mul_f32 v[46:47], v[42:43], v[42:43]
	s_nop 0
	v_fmamk_f32 v46, v46, 0xbdd2d3e2, v251
	v_fmamk_f32 v47, v47, 0xbdd2d3e2, v251
	v_mul_f32_e32 v46, v42, v46
	v_mul_f32_e32 v47, v43, v47
	v_exp_f32_e32 v46, v46
	v_exp_f32_e32 v47, v47
	v_add_f32_e32 v46, 1.0, v46
	v_add_f32_e32 v47, 1.0, v47
	v_rcp_f32_e32 v46, v46
	v_rcp_f32_e32 v47, v47
	s_nop 0
	v_pk_mul_f32 v[42:43], v[42:43], v[46:47]
	v_pk_mul_f32 v[46:47], v[44:45], v[44:45]
	v_cvt_pk_bf16_f32 v42, v42, v43
	v_fmamk_f32 v43, v46, 0xbdd2d3e2, v251
	v_mul_f32_e32 v43, v44, v43
	v_exp_f32_e32 v43, v43
	s_nop 0
	v_add_f32_e32 v43, 1.0, v43
	v_rcp_f32_e32 v46, v43
	v_fmamk_f32 v43, v47, 0xbdd2d3e2, v251
	v_mul_f32_e32 v43, v45, v43
	v_exp_f32_e32 v43, v43
	s_nop 0
	v_add_f32_e32 v43, 1.0, v43
	v_rcp_f32_e32 v47, v43
	s_nop 0
	v_pk_mul_f32 v[44:45], v[44:45], v[46:47]
	s_nop 0
	v_cvt_pk_bf16_f32 v43, v44, v45
	ds_write2_b64 v106, v[62:63], v[42:43] offset0:48 offset1:52
	v_pk_mul_f32 v[42:43], v[38:39], v[38:39]
	s_nop 0
	v_fmamk_f32 v42, v42, 0xbdd2d3e2, v251
	v_fmamk_f32 v43, v43, 0xbdd2d3e2, v251
	v_mul_f32_e32 v42, v38, v42
	v_mul_f32_e32 v43, v39, v43
	v_exp_f32_e32 v42, v42
	v_exp_f32_e32 v43, v43
	v_add_f32_e32 v42, 1.0, v42
	v_add_f32_e32 v43, 1.0, v43
	v_rcp_f32_e32 v42, v42
	v_rcp_f32_e32 v43, v43
	s_nop 0
	v_pk_mul_f32 v[38:39], v[38:39], v[42:43]
	v_pk_mul_f32 v[42:43], v[40:41], v[40:41]
	v_cvt_pk_bf16_f32 v38, v38, v39
	v_fmamk_f32 v39, v42, 0xbdd2d3e2, v251
	v_mul_f32_e32 v39, v40, v39
	v_exp_f32_e32 v39, v39
	s_nop 0
	v_add_f32_e32 v39, 1.0, v39
	v_rcp_f32_e32 v42, v39
	v_fmamk_f32 v39, v43, 0xbdd2d3e2, v251
	v_mul_f32_e32 v39, v41, v39
	v_exp_f32_e32 v39, v39
	s_nop 0
	v_add_f32_e32 v39, 1.0, v39
	v_rcp_f32_e32 v43, v39
	s_nop 0
	v_pk_mul_f32 v[40:41], v[40:41], v[42:43]
	s_nop 0
	v_cvt_pk_bf16_f32 v39, v40, v41
	ds_write2_b64 v102, v[58:59], v[38:39] offset0:80 offset1:84
	v_pk_mul_f32 v[38:39], v[34:35], v[34:35]
	s_nop 0
	v_fmamk_f32 v38, v38, 0xbdd2d3e2, v251
	v_fmamk_f32 v39, v39, 0xbdd2d3e2, v251
	v_mul_f32_e32 v38, v34, v38
	v_mul_f32_e32 v39, v35, v39
	v_exp_f32_e32 v38, v38
	v_exp_f32_e32 v39, v39
	v_add_f32_e32 v38, 1.0, v38
	v_add_f32_e32 v39, 1.0, v39
	v_rcp_f32_e32 v38, v38
	v_rcp_f32_e32 v39, v39
	s_nop 0
	v_pk_mul_f32 v[34:35], v[34:35], v[38:39]
	v_pk_mul_f32 v[38:39], v[36:37], v[36:37]
	v_cvt_pk_bf16_f32 v34, v34, v35
	v_fmamk_f32 v35, v38, 0xbdd2d3e2, v251
	v_mul_f32_e32 v35, v36, v35
	v_exp_f32_e32 v35, v35
	s_nop 0
	v_add_f32_e32 v35, 1.0, v35
	v_rcp_f32_e32 v38, v35
	v_fmamk_f32 v35, v39, 0xbdd2d3e2, v251
	v_mul_f32_e32 v35, v37, v35
	v_exp_f32_e32 v35, v35
	s_nop 0
	v_add_f32_e32 v35, 1.0, v35
	v_rcp_f32_e32 v39, v35
	s_nop 0
	v_pk_mul_f32 v[36:37], v[36:37], v[38:39]
	s_nop 0
	v_cvt_pk_bf16_f32 v35, v36, v37
	global_load_dwordx4 v[36:39], v[118:119], off offset:384
	ds_write2_b64 v100, v[54:55], v[34:35] offset0:112 offset1:116
	s_waitcnt vmcnt(0)
	v_pk_add_f32 v[30:31], v[30:31], v[36:37]
	s_nop 0
	v_pk_mul_f32 v[34:35], v[30:31], v[30:31]
	v_pk_add_f32 v[26:27], v[26:27], v[36:37]
	v_fmamk_f32 v34, v34, 0xbdd2d3e2, v251
	v_fmamk_f32 v35, v35, 0xbdd2d3e2, v251
	v_mul_f32_e32 v34, v30, v34
	v_mul_f32_e32 v35, v31, v35
	v_exp_f32_e32 v34, v34
	v_exp_f32_e32 v35, v35
	v_pk_add_f32 v[22:23], v[22:23], v[36:37]
	v_pk_add_f32 v[18:19], v[18:19], v[36:37]
	v_add_f32_e32 v34, 1.0, v34
	v_add_f32_e32 v35, 1.0, v35
	v_rcp_f32_e32 v34, v34
	v_rcp_f32_e32 v35, v35
	s_nop 0
	v_pk_mul_f32 v[30:31], v[30:31], v[34:35]
	s_nop 0
	v_cvt_pk_bf16_f32 v34, v30, v31
	v_pk_add_f32 v[30:31], v[32:33], v[38:39]
	s_nop 0
	v_pk_mul_f32 v[32:33], v[30:31], v[30:31]
	s_nop 0
	v_fmamk_f32 v32, v32, 0xbdd2d3e2, v251
	v_fmamk_f32 v33, v33, 0xbdd2d3e2, v251
	v_mul_f32_e32 v32, v30, v32
	v_mul_f32_e32 v33, v31, v33
	v_exp_f32_e32 v32, v32
	v_exp_f32_e32 v33, v33
	v_add_f32_e32 v32, 1.0, v32
	v_add_f32_e32 v33, 1.0, v33
	v_rcp_f32_e32 v32, v32
	v_rcp_f32_e32 v33, v33
	s_nop 0
	v_pk_mul_f32 v[30:31], v[30:31], v[32:33]
	s_nop 0
	v_cvt_pk_bf16_f32 v35, v30, v31
	v_pk_mul_f32 v[30:31], v[26:27], v[26:27]
	s_nop 0
	v_fmamk_f32 v30, v30, 0xbdd2d3e2, v251
	v_fmamk_f32 v31, v31, 0xbdd2d3e2, v251
	v_mul_f32_e32 v30, v26, v30
	v_mul_f32_e32 v31, v27, v31
	v_exp_f32_e32 v30, v30
	v_exp_f32_e32 v31, v31
	v_add_f32_e32 v30, 1.0, v30
	v_add_f32_e32 v31, 1.0, v31
	v_rcp_f32_e32 v30, v30
	v_rcp_f32_e32 v31, v31
	s_nop 0
	v_pk_mul_f32 v[26:27], v[26:27], v[30:31]
	s_nop 0
	v_cvt_pk_bf16_f32 v30, v26, v27
	v_pk_add_f32 v[26:27], v[28:29], v[38:39]
	s_nop 0
	v_pk_mul_f32 v[28:29], v[26:27], v[26:27]
	s_nop 0
	v_fmamk_f32 v28, v28, 0xbdd2d3e2, v251
	v_fmamk_f32 v29, v29, 0xbdd2d3e2, v251
	v_mul_f32_e32 v28, v26, v28
	v_mul_f32_e32 v29, v27, v29
	v_exp_f32_e32 v28, v28
	v_exp_f32_e32 v29, v29
	v_add_f32_e32 v28, 1.0, v28
	v_add_f32_e32 v29, 1.0, v29
	v_rcp_f32_e32 v28, v28
	v_rcp_f32_e32 v29, v29
	s_nop 0
	v_pk_mul_f32 v[26:27], v[26:27], v[28:29]
	s_nop 0
	v_cvt_pk_bf16_f32 v31, v26, v27
	v_pk_mul_f32 v[26:27], v[22:23], v[22:23]
	s_nop 0
	v_fmamk_f32 v26, v26, 0xbdd2d3e2, v251
	v_fmamk_f32 v27, v27, 0xbdd2d3e2, v251
	v_mul_f32_e32 v26, v22, v26
	v_mul_f32_e32 v27, v23, v27
	v_exp_f32_e32 v26, v26
	v_exp_f32_e32 v27, v27
	v_add_f32_e32 v26, 1.0, v26
	v_add_f32_e32 v27, 1.0, v27
	v_rcp_f32_e32 v26, v26
	v_rcp_f32_e32 v27, v27
	s_nop 0
	v_pk_mul_f32 v[22:23], v[22:23], v[26:27]
	s_nop 0
	v_cvt_pk_bf16_f32 v26, v22, v23
	v_pk_add_f32 v[22:23], v[24:25], v[38:39]
	s_nop 0
	v_pk_mul_f32 v[24:25], v[22:23], v[22:23]
	s_nop 0
	v_fmamk_f32 v24, v24, 0xbdd2d3e2, v251
	v_fmamk_f32 v25, v25, 0xbdd2d3e2, v251
	v_mul_f32_e32 v24, v22, v24
	v_mul_f32_e32 v25, v23, v25
	v_exp_f32_e32 v24, v24
	v_exp_f32_e32 v25, v25
	v_add_f32_e32 v24, 1.0, v24
	v_add_f32_e32 v25, 1.0, v25
	v_rcp_f32_e32 v24, v24
	v_rcp_f32_e32 v25, v25
	s_nop 0
	v_pk_mul_f32 v[22:23], v[22:23], v[24:25]
	s_nop 0
	v_cvt_pk_bf16_f32 v27, v22, v23
	v_pk_mul_f32 v[22:23], v[18:19], v[18:19]
	s_nop 0
	v_fmamk_f32 v22, v22, 0xbdd2d3e2, v251
	v_fmamk_f32 v23, v23, 0xbdd2d3e2, v251
	v_mul_f32_e32 v22, v18, v22
	v_mul_f32_e32 v23, v19, v23
	v_exp_f32_e32 v22, v22
	v_exp_f32_e32 v23, v23
	v_add_f32_e32 v22, 1.0, v22
	v_add_f32_e32 v23, 1.0, v23
	v_rcp_f32_e32 v22, v22
	v_rcp_f32_e32 v23, v23
	s_nop 0
	v_pk_mul_f32 v[18:19], v[18:19], v[22:23]
	s_nop 0
	v_cvt_pk_bf16_f32 v22, v18, v19
	v_pk_add_f32 v[18:19], v[20:21], v[38:39]
	s_nop 0
	v_pk_mul_f32 v[20:21], v[18:19], v[18:19]
	s_nop 0
	v_fmamk_f32 v20, v20, 0xbdd2d3e2, v251
	v_fmamk_f32 v21, v21, 0xbdd2d3e2, v251
	v_mul_f32_e32 v20, v18, v20
	v_mul_f32_e32 v21, v19, v21
	v_exp_f32_e32 v20, v20
	v_exp_f32_e32 v21, v21
	v_add_f32_e32 v20, 1.0, v20
	v_add_f32_e32 v21, 1.0, v21
	v_rcp_f32_e32 v20, v20
	v_rcp_f32_e32 v21, v21
	s_nop 0
	v_pk_mul_f32 v[18:19], v[18:19], v[20:21]
	s_nop 0
	v_cvt_pk_bf16_f32 v23, v18, v19
	global_load_dwordx4 v[18:21], v[118:119], off offset:448
	s_waitcnt vmcnt(0)
	v_pk_add_f32 v[14:15], v[14:15], v[18:19]
	s_nop 0
	v_pk_mul_f32 v[24:25], v[14:15], v[14:15]
	v_pk_add_f32 v[16:17], v[16:17], v[20:21]
	v_fmamk_f32 v24, v24, 0xbdd2d3e2, v251
	v_fmamk_f32 v25, v25, 0xbdd2d3e2, v251
	v_mul_f32_e32 v24, v14, v24
	v_mul_f32_e32 v25, v15, v25
	v_exp_f32_e32 v24, v24
	v_exp_f32_e32 v25, v25
	v_pk_add_f32 v[10:11], v[10:11], v[18:19]
	v_pk_add_f32 v[12:13], v[12:13], v[20:21]
	v_add_f32_e32 v24, 1.0, v24
	v_add_f32_e32 v25, 1.0, v25
	v_rcp_f32_e32 v24, v24
	v_rcp_f32_e32 v25, v25
	v_pk_add_f32 v[6:7], v[6:7], v[18:19]
	v_pk_add_f32 v[8:9], v[8:9], v[20:21]
	v_pk_add_f32 v[2:3], v[2:3], v[18:19]
	v_pk_mul_f32 v[14:15], v[14:15], v[24:25]
	v_pk_mul_f32 v[24:25], v[16:17], v[16:17]
	v_cvt_pk_bf16_f32 v14, v14, v15
	v_fmamk_f32 v15, v24, 0xbdd2d3e2, v251
	v_mul_f32_e32 v15, v16, v15
	v_exp_f32_e32 v15, v15
	v_pk_add_f32 v[4:5], v[4:5], v[20:21]
	v_add_f32_e32 v15, 1.0, v15
	v_rcp_f32_e32 v24, v15
	v_fmamk_f32 v15, v25, 0xbdd2d3e2, v251
	v_mul_f32_e32 v15, v17, v15
	v_exp_f32_e32 v15, v15
	s_nop 0
	v_add_f32_e32 v15, 1.0, v15
	v_rcp_f32_e32 v25, v15
	s_nop 0
	v_pk_mul_f32 v[16:17], v[16:17], v[24:25]
	s_nop 0
	v_cvt_pk_bf16_f32 v15, v16, v17
	ds_write2_b64 v130, v[34:35], v[14:15] offset0:24 offset1:28
	v_pk_mul_f32 v[14:15], v[10:11], v[10:11]
	v_and_b32_e32 v34, 15, v129
	v_fmamk_f32 v14, v14, 0xbdd2d3e2, v251
	v_fmamk_f32 v15, v15, 0xbdd2d3e2, v251
	v_mul_f32_e32 v14, v10, v14
	v_mul_f32_e32 v15, v11, v15
	v_exp_f32_e32 v14, v14
	v_exp_f32_e32 v15, v15
	v_add_f32_e32 v14, 1.0, v14
	v_add_f32_e32 v15, 1.0, v15
	v_rcp_f32_e32 v14, v14
	v_rcp_f32_e32 v15, v15
	s_nop 0
	v_pk_mul_f32 v[10:11], v[10:11], v[14:15]
	v_pk_mul_f32 v[14:15], v[12:13], v[12:13]
	v_cvt_pk_bf16_f32 v10, v10, v11
	v_fmamk_f32 v11, v14, 0xbdd2d3e2, v251
	v_mul_f32_e32 v11, v12, v11
	v_exp_f32_e32 v11, v11
	s_nop 0
	v_add_f32_e32 v11, 1.0, v11
	v_rcp_f32_e32 v14, v11
	v_fmamk_f32 v11, v15, 0xbdd2d3e2, v251
	v_mul_f32_e32 v11, v13, v11
	v_exp_f32_e32 v11, v11
	s_nop 0
	v_add_f32_e32 v11, 1.0, v11
	v_rcp_f32_e32 v15, v11
	s_nop 0
	v_pk_mul_f32 v[12:13], v[12:13], v[14:15]
	s_nop 0
	v_cvt_pk_bf16_f32 v11, v12, v13
	ds_write2_b64 v106, v[30:31], v[10:11] offset0:56 offset1:60
	v_pk_mul_f32 v[10:11], v[6:7], v[6:7]
	s_nop 0
	v_fmamk_f32 v10, v10, 0xbdd2d3e2, v251
	v_fmamk_f32 v11, v11, 0xbdd2d3e2, v251
	v_mul_f32_e32 v10, v6, v10
	v_mul_f32_e32 v11, v7, v11
	v_exp_f32_e32 v10, v10
	v_exp_f32_e32 v11, v11
	v_add_f32_e32 v10, 1.0, v10
	v_add_f32_e32 v11, 1.0, v11
	v_rcp_f32_e32 v10, v10
	v_rcp_f32_e32 v11, v11
	s_nop 0
	v_pk_mul_f32 v[6:7], v[6:7], v[10:11]
	v_pk_mul_f32 v[10:11], v[8:9], v[8:9]
	v_cvt_pk_bf16_f32 v6, v6, v7
	v_fmamk_f32 v7, v10, 0xbdd2d3e2, v251
	v_mul_f32_e32 v7, v8, v7
	v_exp_f32_e32 v7, v7
	s_nop 0
	v_add_f32_e32 v7, 1.0, v7
	v_rcp_f32_e32 v10, v7
	v_fmamk_f32 v7, v11, 0xbdd2d3e2, v251
	v_mul_f32_e32 v7, v9, v7
	v_exp_f32_e32 v7, v7
	s_nop 0
	v_add_f32_e32 v7, 1.0, v7
	v_rcp_f32_e32 v11, v7
	s_nop 0
	v_pk_mul_f32 v[8:9], v[8:9], v[10:11]
	s_nop 0
	v_cvt_pk_bf16_f32 v7, v8, v9
	ds_write2_b64 v102, v[26:27], v[6:7] offset0:88 offset1:92
	v_pk_mul_f32 v[6:7], v[2:3], v[2:3]
	v_lshl_add_u64 v[10:11], s[40:41], 0, v[0:1]
	v_fmamk_f32 v6, v6, 0xbdd2d3e2, v251
	v_fmamk_f32 v7, v7, 0xbdd2d3e2, v251
	v_mul_f32_e32 v6, v2, v6
	v_mul_f32_e32 v7, v3, v7
	v_exp_f32_e32 v6, v6
	v_exp_f32_e32 v7, v7
	v_lshl_add_u64 v[68:69], v[10:11], 0, 64
	v_add_f32_e32 v6, 1.0, v6
	v_add_f32_e32 v7, 1.0, v7
	v_rcp_f32_e32 v6, v6
	v_rcp_f32_e32 v7, v7
	s_nop 0
	v_pk_mul_f32 v[2:3], v[2:3], v[6:7]
	v_pk_mul_f32 v[6:7], v[4:5], v[4:5]
	v_cvt_pk_bf16_f32 v2, v2, v3
	v_fmamk_f32 v3, v6, 0xbdd2d3e2, v251
	v_mul_f32_e32 v3, v4, v3
	v_exp_f32_e32 v3, v3
	s_nop 0
	v_add_f32_e32 v3, 1.0, v3
	v_rcp_f32_e32 v6, v3
	v_fmamk_f32 v3, v7, 0xbdd2d3e2, v251
	v_mul_f32_e32 v3, v5, v3
	v_exp_f32_e32 v3, v3
	s_nop 0
	v_add_f32_e32 v3, 1.0, v3
	v_rcp_f32_e32 v7, v3
	s_nop 0
	v_pk_mul_f32 v[4:5], v[4:5], v[6:7]
	s_nop 0
	v_cvt_pk_bf16_f32 v3, v4, v5
	ds_write2_b64 v100, v[22:23], v[2:3] offset0:120 offset1:124
	v_ashrrev_i32_e32 v2, 1, v129
	v_and_b32_e32 v35, 0xffffffe0, v2
	v_or_b32_e32 v2, v35, v34
	v_lshlrev_b32_e32 v6, 9, v34
	v_mad_u64_u32 v[12:13], s[0:1], v2, s0, v[0:1]
	v_mov_b32_e32 v7, v1
	v_or_b32_e32 v2, 0x2000, v6
	v_mov_b32_e32 v3, v1
	v_lshl_add_u64 v[8:9], v[10:11], 0, v[6:7]
	v_lshl_add_u64 v[4:5], v[10:11], 0, v[2:3]
	s_waitcnt lgkmcnt(0)
	s_barrier
	ds_read_b128 v[14:17], v12
	ds_read_b128 v[18:21], v12 offset:8448
	global_load_dwordx4 v[22:25], v[8:9], off
	global_load_dwordx4 v[26:29], v[4:5], off
	v_or_b32_e32 v4, 0x4000, v6
	v_mov_b32_e32 v5, v1
	v_or_b32_e32 v6, 0x6000, v6
	v_lshl_add_u64 v[30:31], v[10:11], 0, v[4:5]
	v_lshl_add_u64 v[36:37], v[10:11], 0, v[6:7]
	global_load_dwordx4 v[30:33], v[30:31], off
	v_lshl_add_u64 v[60:61], v[68:69], 0, v[2:3]
	global_load_dwordx4 v[36:39], v[36:37], off
	v_lshl_add_u64 v[64:65], v[68:69], 0, v[4:5]
	v_lshl_add_u64 v[68:69], v[68:69], 0, v[6:7]
	s_waitcnt vmcnt(3) lgkmcnt(1)
	v_mfma_f32_16x16x32_bf16 v[40:43], v[22:25], v[14:17], 0
	s_mov_b64 s[0:1], 0xc0
	v_or_b32_e32 v34, s12, v34
	s_mov_b64 s[12:13], -1
	s_waitcnt lgkmcnt(0)
	v_mfma_f32_16x16x32_bf16 v[22:25], v[22:25], v[18:21], 0
	s_waitcnt vmcnt(2)
	v_mfma_f32_16x16x32_bf16 v[44:47], v[26:29], v[14:17], 0
	v_mfma_f32_16x16x32_bf16 v[26:29], v[26:29], v[18:21], 0
	s_waitcnt vmcnt(1)
	v_mfma_f32_16x16x32_bf16 v[48:51], v[30:33], v[14:17], 0
	v_mfma_f32_16x16x32_bf16 v[30:33], v[30:33], v[18:21], 0
	s_waitcnt vmcnt(0)
	v_mfma_f32_16x16x32_bf16 v[14:17], v[36:39], v[14:17], 0
	v_mfma_f32_16x16x32_bf16 v[18:21], v[36:39], v[18:21], 0
	ds_read_b128 v[36:39], v12 offset:64
	ds_read_b128 v[52:55], v12 offset:8512
	global_load_dwordx4 v[64:67], v[64:65], off
	s_nop 0
	global_load_dwordx4 v[68:71], v[68:69], off
	s_waitcnt vmcnt(0) lgkmcnt(1)
	v_mfma_f32_16x16x32_bf16 v[14:17], v[68:71], v[36:39], v[14:17]
	global_load_dwordx4 v[56:59], v[8:9], off offset:64
	s_nop 0
	global_load_dwordx4 v[60:63], v[60:61], off
	s_waitcnt lgkmcnt(0)
	v_mfma_f32_16x16x32_bf16 v[18:21], v[68:71], v[52:55], v[18:21]
	v_lshl_add_u64 v[68:69], v[10:11], 0, s[6:7]
	s_waitcnt vmcnt(0)
	v_mfma_f32_16x16x32_bf16 v[44:47], v[60:63], v[36:39], v[44:47]
	v_mfma_f32_16x16x32_bf16 v[26:29], v[60:63], v[52:55], v[26:29]
	v_lshl_add_u64 v[60:61], v[68:69], 0, v[2:3]
	v_mfma_f32_16x16x32_bf16 v[48:51], v[64:67], v[36:39], v[48:51]
	v_mfma_f32_16x16x32_bf16 v[30:33], v[64:67], v[52:55], v[30:33]
	v_lshl_add_u64 v[64:65], v[68:69], 0, v[4:5]
	v_lshl_add_u64 v[68:69], v[68:69], 0, v[6:7]
	v_mfma_f32_16x16x32_bf16 v[40:43], v[56:59], v[36:39], v[40:43]
	v_mfma_f32_16x16x32_bf16 v[22:25], v[56:59], v[52:55], v[22:25]
	ds_read_b128 v[36:39], v12 offset:128
	ds_read_b128 v[52:55], v12 offset:8576
	global_load_dwordx4 v[64:67], v[64:65], off
	s_nop 0
	global_load_dwordx4 v[68:71], v[68:69], off
	s_waitcnt vmcnt(0) lgkmcnt(1)
	v_mfma_f32_16x16x32_bf16 v[14:17], v[68:71], v[36:39], v[14:17]
	global_load_dwordx4 v[56:59], v[8:9], off offset:128
	s_nop 0
	global_load_dwordx4 v[60:63], v[60:61], off
	s_waitcnt lgkmcnt(0)
	v_mfma_f32_16x16x32_bf16 v[18:21], v[68:71], v[52:55], v[18:21]
	v_lshl_add_u64 v[68:69], v[10:11], 0, s[0:1]
	s_mov_b64 s[0:1], 0x100
	s_waitcnt vmcnt(0)
	v_mfma_f32_16x16x32_bf16 v[44:47], v[60:63], v[36:39], v[44:47]
	v_mfma_f32_16x16x32_bf16 v[26:29], v[60:63], v[52:55], v[26:29]
	v_lshl_add_u64 v[60:61], v[68:69], 0, v[2:3]
	v_mfma_f32_16x16x32_bf16 v[48:51], v[64:67], v[36:39], v[48:51]
	v_mfma_f32_16x16x32_bf16 v[30:33], v[64:67], v[52:55], v[30:33]
	v_lshl_add_u64 v[64:65], v[68:69], 0, v[4:5]
	v_lshl_add_u64 v[68:69], v[68:69], 0, v[6:7]
	v_mfma_f32_16x16x32_bf16 v[40:43], v[56:59], v[36:39], v[40:43]
	v_mfma_f32_16x16x32_bf16 v[22:25], v[56:59], v[52:55], v[22:25]
	ds_read_b128 v[36:39], v12 offset:192
	ds_read_b128 v[52:55], v12 offset:8640
	global_load_dwordx4 v[64:67], v[64:65], off
	s_nop 0
	global_load_dwordx4 v[68:71], v[68:69], off
	s_waitcnt vmcnt(0) lgkmcnt(1)
	v_mfma_f32_16x16x32_bf16 v[14:17], v[68:71], v[36:39], v[14:17]
	global_load_dwordx4 v[56:59], v[8:9], off offset:192
	s_nop 0
	global_load_dwordx4 v[60:63], v[60:61], off
	s_waitcnt lgkmcnt(0)
	v_mfma_f32_16x16x32_bf16 v[18:21], v[68:71], v[52:55], v[18:21]
	v_lshl_add_u64 v[68:69], v[10:11], 0, s[0:1]
	s_mov_b64 s[0:1], 0x140
	s_waitcnt vmcnt(0)
	v_mfma_f32_16x16x32_bf16 v[44:47], v[60:63], v[36:39], v[44:47]
	v_mfma_f32_16x16x32_bf16 v[26:29], v[60:63], v[52:55], v[26:29]
	v_lshl_add_u64 v[60:61], v[68:69], 0, v[2:3]
	v_mfma_f32_16x16x32_bf16 v[48:51], v[64:67], v[36:39], v[48:51]
	v_mfma_f32_16x16x32_bf16 v[30:33], v[64:67], v[52:55], v[30:33]
	v_lshl_add_u64 v[64:65], v[68:69], 0, v[4:5]
	v_lshl_add_u64 v[68:69], v[68:69], 0, v[6:7]
	v_mfma_f32_16x16x32_bf16 v[40:43], v[56:59], v[36:39], v[40:43]
	v_mfma_f32_16x16x32_bf16 v[22:25], v[56:59], v[52:55], v[22:25]
	ds_read_b128 v[36:39], v12 offset:256
	ds_read_b128 v[52:55], v12 offset:8704
	global_load_dwordx4 v[64:67], v[64:65], off
	s_nop 0
	global_load_dwordx4 v[68:71], v[68:69], off
	s_waitcnt vmcnt(0) lgkmcnt(1)
	v_mfma_f32_16x16x32_bf16 v[14:17], v[68:71], v[36:39], v[14:17]
	global_load_dwordx4 v[56:59], v[8:9], off offset:256
	s_nop 0
	global_load_dwordx4 v[60:63], v[60:61], off
	s_waitcnt lgkmcnt(0)
	v_mfma_f32_16x16x32_bf16 v[18:21], v[68:71], v[52:55], v[18:21]
	v_lshl_add_u64 v[68:69], v[10:11], 0, s[0:1]
	s_mov_b64 s[0:1], 0x180
	s_waitcnt vmcnt(0)
	v_mfma_f32_16x16x32_bf16 v[44:47], v[60:63], v[36:39], v[44:47]
	v_mfma_f32_16x16x32_bf16 v[26:29], v[60:63], v[52:55], v[26:29]
	v_lshl_add_u64 v[60:61], v[68:69], 0, v[2:3]
	v_mfma_f32_16x16x32_bf16 v[48:51], v[64:67], v[36:39], v[48:51]
	v_mfma_f32_16x16x32_bf16 v[30:33], v[64:67], v[52:55], v[30:33]
	v_lshl_add_u64 v[64:65], v[68:69], 0, v[4:5]
	v_lshl_add_u64 v[68:69], v[68:69], 0, v[6:7]
	v_mfma_f32_16x16x32_bf16 v[40:43], v[56:59], v[36:39], v[40:43]
	v_mfma_f32_16x16x32_bf16 v[22:25], v[56:59], v[52:55], v[22:25]
	ds_read_b128 v[36:39], v12 offset:320
	ds_read_b128 v[52:55], v12 offset:8768
	global_load_dwordx4 v[64:67], v[64:65], off
	s_nop 0
	global_load_dwordx4 v[68:71], v[68:69], off
	s_waitcnt vmcnt(0) lgkmcnt(1)
	v_mfma_f32_16x16x32_bf16 v[14:17], v[68:71], v[36:39], v[14:17]
	global_load_dwordx4 v[56:59], v[8:9], off offset:320
	s_nop 0
	global_load_dwordx4 v[60:63], v[60:61], off
	s_waitcnt lgkmcnt(0)
	v_mfma_f32_16x16x32_bf16 v[18:21], v[68:71], v[52:55], v[18:21]
	v_lshl_add_u64 v[68:69], v[10:11], 0, s[0:1]
	s_mov_b64 s[0:1], 0x1c0
	s_waitcnt vmcnt(0)
	v_mfma_f32_16x16x32_bf16 v[44:47], v[60:63], v[36:39], v[44:47]
	v_mfma_f32_16x16x32_bf16 v[26:29], v[60:63], v[52:55], v[26:29]
	v_lshl_add_u64 v[60:61], v[68:69], 0, v[2:3]
	v_mfma_f32_16x16x32_bf16 v[48:51], v[64:67], v[36:39], v[48:51]
	v_mfma_f32_16x16x32_bf16 v[30:33], v[64:67], v[52:55], v[30:33]
	v_lshl_add_u64 v[64:65], v[68:69], 0, v[4:5]
	v_lshl_add_u64 v[68:69], v[68:69], 0, v[6:7]
	v_mfma_f32_16x16x32_bf16 v[40:43], v[56:59], v[36:39], v[40:43]
	v_mfma_f32_16x16x32_bf16 v[22:25], v[56:59], v[52:55], v[22:25]
	ds_read_b128 v[36:39], v12 offset:384
	ds_read_b128 v[52:55], v12 offset:8832
	global_load_dwordx4 v[56:59], v[8:9], off offset:384
	s_nop 0
	global_load_dwordx4 v[60:63], v[60:61], off
	s_waitcnt vmcnt(1) lgkmcnt(1)
	v_mfma_f32_16x16x32_bf16 v[40:43], v[56:59], v[36:39], v[40:43]
	global_load_dwordx4 v[64:67], v[64:65], off
	s_nop 0
	global_load_dwordx4 v[68:71], v[68:69], off
	s_waitcnt vmcnt(2)
	v_mfma_f32_16x16x32_bf16 v[44:47], v[60:63], v[36:39], v[44:47]
	s_waitcnt vmcnt(1)
	v_mfma_f32_16x16x32_bf16 v[48:51], v[64:67], v[36:39], v[48:51]
	s_waitcnt vmcnt(0)
	v_mfma_f32_16x16x32_bf16 v[36:39], v[68:71], v[36:39], v[14:17]
	s_nop 2
	v_lshl_add_u64 v[16:17], v[10:11], 0, s[0:1]
	v_lshl_add_u64 v[2:3], v[16:17], 0, v[2:3]
	v_lshl_add_u64 v[6:7], v[16:17], 0, v[6:7]
	s_waitcnt lgkmcnt(0)
	v_mfma_f32_16x16x32_bf16 v[22:25], v[56:59], v[52:55], v[22:25]
	s_cselect_b64 s[0:1], -1, 0
	s_and_b64 vcc, exec, s[0:1]
	v_mfma_f32_16x16x32_bf16 v[56:59], v[60:63], v[52:55], v[26:29]
	v_mfma_f32_16x16x32_bf16 v[60:63], v[64:67], v[52:55], v[30:33]
	v_mfma_f32_16x16x32_bf16 v[52:55], v[68:71], v[52:55], v[18:21]
	ds_read_b128 v[64:67], v12 offset:448
	ds_read_b128 v[68:71], v12 offset:8896
	global_load_dwordx4 v[8:11], v[8:9], off offset:448
	s_nop 0
	global_load_dwordx4 v[12:15], v[2:3], off
	global_load_dwordx4 v[72:75], v[6:7], off
	v_lshl_add_u64 v[2:3], v[16:17], 0, v[4:5]
	global_load_dwordx4 v[2:5], v[2:3], off
	s_waitcnt vmcnt(3) lgkmcnt(1)
	v_mfma_f32_16x16x32_bf16 v[30:33], v[8:11], v[64:67], v[40:43]
	s_nop 2
	v_or_b32_e32 v43, 3, v128
	s_waitcnt lgkmcnt(0)
	v_mfma_f32_16x16x32_bf16 v[26:29], v[8:11], v[68:71], v[22:25]
	s_waitcnt vmcnt(1)
	v_mfma_f32_16x16x32_bf16 v[6:9], v[72:75], v[64:67], v[36:39]
	s_nop 2
	v_add_u32_e32 v39, v34, v35
	v_ashrrev_i32_e32 v34, 9, v39
	v_mfma_f32_16x16x32_bf16 v[22:25], v[12:15], v[64:67], v[44:47]
	v_bfi_b32 v34, -4, v34, v129
	v_ashrrev_i32_e32 v35, 31, v34
	v_lshlrev_b64 v[36:37], 15, v[34:35]
	v_mfma_f32_16x16x32_bf16 v[18:21], v[12:15], v[68:71], v[56:59]
	v_lshrrev_b32_e32 v47, 2, v39
	v_and_b32_e32 v40, 0x1fb, v47
	v_lshlrev_b32_e32 v38, 1, v39
	s_waitcnt vmcnt(0)
	v_mfma_f32_16x16x32_bf16 v[14:17], v[2:5], v[64:67], v[48:51]
	v_lshrrev_b32_e32 v34, 3, v39
	v_bfe_u32 v35, v39, 2, 2
	v_lshlrev_b32_e32 v39, 2, v40
	v_mfma_f32_16x16x32_bf16 v[10:13], v[2:5], v[68:71], v[60:63]
	v_or_b32_e32 v45, 1, v128
	v_or_b32_e32 v44, 2, v128
	v_and_b32_e32 v46, 0xe00, v38
	v_mfma_f32_16x16x32_bf16 v[2:5], v[72:75], v[68:71], v[52:55]
	v_and_or_b32 v40, v34, 4, v35
	v_and_b32_e32 v41, 0xc0, v39
	v_lshl_add_u64 v[34:35], v[36:37], 1, s[48:49]
	s_cbranch_vccz .LBB0_599
	v_or3_b32 v42, v128, v46, v41
	v_lshlrev_b32_e32 v48, 4, v42
	v_mov_b32_e32 v49, v1
	v_lshl_add_u64 v[48:49], v[34:35], 0, v[48:49]
	v_lshlrev_b32_e32 v50, 1, v40
	v_mov_b32_e32 v51, v1
	v_cvt_pk_bf16_f32 v39, v30, s0
	v_lshl_add_u64 v[48:49], v[48:49], 0, v[50:51]
	v_or3_b32 v42, v45, v46, v41
	global_store_short v[48:49], v39, off
	v_lshlrev_b32_e32 v48, 4, v42
	v_mov_b32_e32 v49, v1
	v_lshl_add_u64 v[48:49], v[34:35], 0, v[48:49]
	v_cvt_pk_bf16_f32 v39, v31, s0
	v_lshl_add_u64 v[48:49], v[48:49], 0, v[50:51]
	v_or3_b32 v42, v44, v46, v41
	global_store_short v[48:49], v39, off
	v_lshlrev_b32_e32 v48, 4, v42
	v_mov_b32_e32 v49, v1
	v_lshl_add_u64 v[48:49], v[34:35], 0, v[48:49]
	v_cvt_pk_bf16_f32 v39, v32, s0
	v_lshl_add_u64 v[48:49], v[48:49], 0, v[50:51]
	v_or3_b32 v42, v43, v46, v41
	global_store_short v[48:49], v39, off
	v_lshlrev_b32_e32 v48, 4, v42
	v_mov_b32_e32 v49, v1
	v_lshl_add_u64 v[48:49], v[34:35], 0, v[48:49]
	v_cvt_pk_bf16_f32 v39, v33, s0
	v_lshl_add_u64 v[48:49], v[48:49], 0, v[50:51]
	global_store_short v[48:49], v39, off
	s_mov_b64 s[12:13], 0
